# MO8+TRIM+Z0b: no accumulator zeroing (srcC=0 segment copies for the first K-iteration), first-iteration branch placed ahead of the load segment's waits
# speedup vs baseline: 1.0030x; 1.0013x over previous
.LBB0_139:
	s_add_u32 s22, s18, 0xfff00080
	s_addc_u32 s23, s19, -1
	s_add_i32 s49, 0, 0x10000
	s_cmp_eq_u32 s48, 60
	s_cselect_b32 s25, s9, s23
	s_cselect_b32 s24, s44, s22
	s_cselect_b32 s23, s7, s47
	s_cselect_b32 s22, s45, s46
	s_add_i32 s52, 0, 0x14000
	v_add_u32_e32 v156, s49, v145
	v_add_u32_e32 v172, s52, v145
	ds_read_b128 v[140:143], v156
	ds_read_b128 v[148:151], v156 offset:1024
	ds_read_b128 v[152:155], v156 offset:2048
	ds_read_b128 v[156:159], v156 offset:3072
	ds_read_b128 v[160:163], v172
	ds_read_b128 v[164:167], v172 offset:1024
	ds_read_b128 v[168:171], v172 offset:2048
	ds_read_b128 v[190:193], v172 offset:3072
	v_lshl_add_u64 v[172:173], s[18:19], 0, v[136:137]
	s_add_i32 m0, s31, 0xc000
	ds_read_b128 v[194:197], v147
	ds_read_b128 v[198:201], v147 offset:1024
	ds_read_b128 v[202:205], v147 offset:2048
	ds_read_b128 v[206:209], v147 offset:3072
	ds_read_b128 v[228:231], v147 offset:4096
	ds_read_b128 v[232:235], v147 offset:5120
	ds_read_b128 v[236:239], v147 offset:6144
	ds_read_b128 v[240:243], v147 offset:7168
	global_load_lds_dwordx4 v[172:173], off
	v_lshl_add_u64 v[172:173], s[18:19], 0, v[138:139]
	s_add_i32 m0, s31, 0xe000
	s_nop 0
	global_load_lds_dwordx4 v[172:173], off
	s_cmp_eq_u32 s48, -2
	s_cbranch_scc1 .Lz0_0_0
	s_waitcnt vmcnt(8)
	s_waitcnt lgkmcnt(0)
	s_setprio 1
	s_barrier
	v_mfma_f32_16x16x32_bf16 v[126:129], v[140:143], v[194:197], v[126:129]
	v_mfma_f32_16x16x32_bf16 v[126:129], v[148:151], v[198:201], v[126:129]
	v_mfma_f32_16x16x32_bf16 v[118:121], v[148:151], v[206:209], v[118:121]
	v_mfma_f32_16x16x32_bf16 v[118:121], v[140:143], v[202:205], v[118:121]
	v_mfma_f32_16x16x32_bf16 v[102:105], v[140:143], v[228:231], v[102:105]
	v_mfma_f32_16x16x32_bf16 v[102:105], v[148:151], v[232:235], v[102:105]
	v_mfma_f32_16x16x32_bf16 v[86:89], v[148:151], v[240:243], v[86:89]
	v_mfma_f32_16x16x32_bf16 v[86:89], v[140:143], v[236:239], v[86:89]
	v_mfma_f32_16x16x32_bf16 v[78:81], v[152:155], v[236:239], v[78:81]
	v_mfma_f32_16x16x32_bf16 v[78:81], v[156:159], v[240:243], v[78:81]
	v_mfma_f32_16x16x32_bf16 v[94:97], v[156:159], v[232:235], v[94:97]
	v_mfma_f32_16x16x32_bf16 v[94:97], v[152:155], v[228:231], v[94:97]
	v_mfma_f32_16x16x32_bf16 v[110:113], v[152:155], v[202:205], v[110:113]
	v_mfma_f32_16x16x32_bf16 v[110:113], v[156:159], v[206:209], v[110:113]
	v_mfma_f32_16x16x32_bf16 v[122:125], v[156:159], v[198:201], v[122:125]
	v_mfma_f32_16x16x32_bf16 v[122:125], v[152:155], v[194:197], v[122:125]
	v_mfma_f32_16x16x32_bf16 v[114:117], v[160:163], v[194:197], v[114:117]
	v_mfma_f32_16x16x32_bf16 v[114:117], v[164:167], v[198:201], v[114:117]
	v_mfma_f32_16x16x32_bf16 v[98:101], v[164:167], v[206:209], v[98:101]
	v_mfma_f32_16x16x32_bf16 v[98:101], v[160:163], v[202:205], v[98:101]
	v_mfma_f32_16x16x32_bf16 v[82:85], v[160:163], v[228:231], v[82:85]
	v_mfma_f32_16x16x32_bf16 v[82:85], v[164:167], v[232:235], v[82:85]
	v_mfma_f32_16x16x32_bf16 v[70:73], v[164:167], v[240:243], v[70:73]
	v_mfma_f32_16x16x32_bf16 v[70:73], v[160:163], v[236:239], v[70:73]
	v_mfma_f32_16x16x32_bf16 v[66:69], v[168:171], v[236:239], v[66:69]
	v_mfma_f32_16x16x32_bf16 v[66:69], v[190:193], v[240:243], v[66:69]
	v_mfma_f32_16x16x32_bf16 v[74:77], v[190:193], v[232:235], v[74:77]
	v_mfma_f32_16x16x32_bf16 v[74:77], v[168:171], v[228:231], v[74:77]
	v_mfma_f32_16x16x32_bf16 v[90:93], v[168:171], v[202:205], v[90:93]
	v_mfma_f32_16x16x32_bf16 v[90:93], v[190:193], v[206:209], v[90:93]
	v_mfma_f32_16x16x32_bf16 v[106:109], v[190:193], v[198:201], v[106:109]
	v_mfma_f32_16x16x32_bf16 v[106:109], v[168:171], v[194:197], v[106:109]
	s_barrier
	s_setprio 0
.Lz0_0_0_ret:
	s_add_i32 s49, s49, s26
	v_lshl_add_u64 v[172:173], s[22:23], 0, v[0:1]
	s_mov_b32 m0, s49
	ds_read_b128 v[194:197], v147 offset:16384
	ds_read_b128 v[198:201], v147 offset:17408
	ds_read_b128 v[202:205], v147 offset:18432
	ds_read_b128 v[206:209], v147 offset:19456
	ds_read_b128 v[228:231], v147 offset:20480
	ds_read_b128 v[232:235], v147 offset:21504
	ds_read_b128 v[236:239], v147 offset:22528
	ds_read_b128 v[240:243], v147 offset:23552
	global_load_lds_dwordx4 v[172:173], off
	s_add_i32 m0, s49, 0x2000
	s_add_u32 s50, s22, 0x100000
	v_lshl_add_u64 v[178:179], s[22:23], 0, v[130:131]
	s_addc_u32 s51, s23, 0
	s_add_i32 s49, s52, s26
	global_load_lds_dwordx4 v[178:179], off
	v_lshl_add_u64 v[180:181], s[50:51], 0, v[0:1]
	s_mov_b32 m0, s49
	v_lshl_add_u64 v[210:211], s[24:25], 0, v[132:133]
	global_load_lds_dwordx4 v[180:181], off
	v_lshl_add_u64 v[180:181], s[50:51], 0, v[130:131]
	s_add_i32 m0, s49, 0x2000
	s_nop 0
	global_load_lds_dwordx4 v[180:181], off
	v_lshl_add_u64 v[180:181], s[24:25], 0, v[134:135]
	s_mov_b32 m0, s31
	s_nop 0
	global_load_lds_dwordx4 v[180:181], off
	s_mov_b32 m0, s36
	s_nop 0
	global_load_lds_dwordx4 v[210:211], off
	s_cmp_eq_u32 s48, -2
	s_cbranch_scc1 .Lz0_0_1
	s_waitcnt vmcnt(8)
	s_waitcnt lgkmcnt(0)
	s_setprio 1
	s_barrier
	v_mfma_f32_16x16x32_bf16 v[62:65], v[140:143], v[194:197], v[62:65]
	v_mfma_f32_16x16x32_bf16 v[62:65], v[148:151], v[198:201], v[62:65]
	v_mfma_f32_16x16x32_bf16 v[54:57], v[148:151], v[206:209], v[54:57]
	v_mfma_f32_16x16x32_bf16 v[54:57], v[140:143], v[202:205], v[54:57]
	v_mfma_f32_16x16x32_bf16 v[38:41], v[140:143], v[228:231], v[38:41]
	v_mfma_f32_16x16x32_bf16 v[38:41], v[148:151], v[232:235], v[38:41]
	v_mfma_f32_16x16x32_bf16 v[22:25], v[148:151], v[240:243], v[22:25]
	v_mfma_f32_16x16x32_bf16 v[22:25], v[140:143], v[236:239], v[22:25]
	v_mfma_f32_16x16x32_bf16 v[14:17], v[152:155], v[236:239], v[14:17]
	v_mfma_f32_16x16x32_bf16 v[14:17], v[156:159], v[240:243], v[14:17]
	v_mfma_f32_16x16x32_bf16 v[30:33], v[156:159], v[232:235], v[30:33]
	v_mfma_f32_16x16x32_bf16 v[30:33], v[152:155], v[228:231], v[30:33]
	v_mfma_f32_16x16x32_bf16 v[46:49], v[152:155], v[202:205], v[46:49]
	v_mfma_f32_16x16x32_bf16 v[46:49], v[156:159], v[206:209], v[46:49]
	v_mfma_f32_16x16x32_bf16 v[58:61], v[156:159], v[198:201], v[58:61]
	v_mfma_f32_16x16x32_bf16 v[58:61], v[152:155], v[194:197], v[58:61]
	v_mfma_f32_16x16x32_bf16 v[50:53], v[160:163], v[194:197], v[50:53]
	v_mfma_f32_16x16x32_bf16 v[50:53], v[164:167], v[198:201], v[50:53]
	v_mfma_f32_16x16x32_bf16 v[34:37], v[164:167], v[206:209], v[34:37]
	v_mfma_f32_16x16x32_bf16 v[34:37], v[160:163], v[202:205], v[34:37]
	v_mfma_f32_16x16x32_bf16 v[18:21], v[160:163], v[228:231], v[18:21]
	v_mfma_f32_16x16x32_bf16 v[18:21], v[164:167], v[232:235], v[18:21]
	v_mfma_f32_16x16x32_bf16 v[6:9], v[164:167], v[240:243], v[6:9]
	v_mfma_f32_16x16x32_bf16 v[6:9], v[160:163], v[236:239], v[6:9]
	v_mfma_f32_16x16x32_bf16 v[2:5], v[168:171], v[236:239], v[2:5]
	v_mfma_f32_16x16x32_bf16 v[2:5], v[190:193], v[240:243], v[2:5]
	v_mfma_f32_16x16x32_bf16 v[10:13], v[190:193], v[232:235], v[10:13]
	v_mfma_f32_16x16x32_bf16 v[10:13], v[168:171], v[228:231], v[10:13]
	v_mfma_f32_16x16x32_bf16 v[26:29], v[168:171], v[202:205], v[26:29]
	v_mfma_f32_16x16x32_bf16 v[26:29], v[190:193], v[206:209], v[26:29]
	v_mfma_f32_16x16x32_bf16 v[42:45], v[190:193], v[198:201], v[42:45]
	v_mfma_f32_16x16x32_bf16 v[42:45], v[168:171], v[194:197], v[42:45]
	s_barrier
	s_setprio 0

.Lz0_0_0:
	s_waitcnt vmcnt(8)
	s_waitcnt lgkmcnt(0)
	s_setprio 1
	s_barrier
	v_mfma_f32_16x16x32_bf16 v[126:129], v[140:143], v[194:197], 0
	v_mfma_f32_16x16x32_bf16 v[126:129], v[148:151], v[198:201], v[126:129]
	v_mfma_f32_16x16x32_bf16 v[118:121], v[148:151], v[206:209], 0
	v_mfma_f32_16x16x32_bf16 v[118:121], v[140:143], v[202:205], v[118:121]
	v_mfma_f32_16x16x32_bf16 v[102:105], v[140:143], v[228:231], 0
	v_mfma_f32_16x16x32_bf16 v[102:105], v[148:151], v[232:235], v[102:105]
	v_mfma_f32_16x16x32_bf16 v[86:89], v[148:151], v[240:243], 0
	v_mfma_f32_16x16x32_bf16 v[86:89], v[140:143], v[236:239], v[86:89]
	v_mfma_f32_16x16x32_bf16 v[78:81], v[152:155], v[236:239], 0
	v_mfma_f32_16x16x32_bf16 v[78:81], v[156:159], v[240:243], v[78:81]
	v_mfma_f32_16x16x32_bf16 v[94:97], v[156:159], v[232:235], 0
	v_mfma_f32_16x16x32_bf16 v[94:97], v[152:155], v[228:231], v[94:97]
	v_mfma_f32_16x16x32_bf16 v[110:113], v[152:155], v[202:205], 0
	v_mfma_f32_16x16x32_bf16 v[110:113], v[156:159], v[206:209], v[110:113]
	v_mfma_f32_16x16x32_bf16 v[122:125], v[156:159], v[198:201], 0
	v_mfma_f32_16x16x32_bf16 v[122:125], v[152:155], v[194:197], v[122:125]
	v_mfma_f32_16x16x32_bf16 v[114:117], v[160:163], v[194:197], 0
	v_mfma_f32_16x16x32_bf16 v[114:117], v[164:167], v[198:201], v[114:117]
	v_mfma_f32_16x16x32_bf16 v[98:101], v[164:167], v[206:209], 0
	v_mfma_f32_16x16x32_bf16 v[98:101], v[160:163], v[202:205], v[98:101]
	v_mfma_f32_16x16x32_bf16 v[82:85], v[160:163], v[228:231], 0
	v_mfma_f32_16x16x32_bf16 v[82:85], v[164:167], v[232:235], v[82:85]
	v_mfma_f32_16x16x32_bf16 v[70:73], v[164:167], v[240:243], 0
	v_mfma_f32_16x16x32_bf16 v[70:73], v[160:163], v[236:239], v[70:73]
	v_mfma_f32_16x16x32_bf16 v[66:69], v[168:171], v[236:239], 0
	v_mfma_f32_16x16x32_bf16 v[66:69], v[190:193], v[240:243], v[66:69]
	v_mfma_f32_16x16x32_bf16 v[74:77], v[190:193], v[232:235], 0
	v_mfma_f32_16x16x32_bf16 v[74:77], v[168:171], v[228:231], v[74:77]
	v_mfma_f32_16x16x32_bf16 v[90:93], v[168:171], v[202:205], 0
	v_mfma_f32_16x16x32_bf16 v[90:93], v[190:193], v[206:209], v[90:93]
	v_mfma_f32_16x16x32_bf16 v[106:109], v[190:193], v[198:201], 0
	v_mfma_f32_16x16x32_bf16 v[106:109], v[168:171], v[194:197], v[106:109]
	s_barrier
	s_setprio 0
	s_branch .Lz0_0_0_ret
.Lz0_0_1:
	s_waitcnt vmcnt(8)
	s_waitcnt lgkmcnt(0)
	s_setprio 1
	s_barrier
	v_mfma_f32_16x16x32_bf16 v[62:65], v[140:143], v[194:197], 0
	v_mfma_f32_16x16x32_bf16 v[62:65], v[148:151], v[198:201], v[62:65]
	v_mfma_f32_16x16x32_bf16 v[54:57], v[148:151], v[206:209], 0
	v_mfma_f32_16x16x32_bf16 v[54:57], v[140:143], v[202:205], v[54:57]
	v_mfma_f32_16x16x32_bf16 v[38:41], v[140:143], v[228:231], 0
	v_mfma_f32_16x16x32_bf16 v[38:41], v[148:151], v[232:235], v[38:41]
	v_mfma_f32_16x16x32_bf16 v[22:25], v[148:151], v[240:243], 0
	v_mfma_f32_16x16x32_bf16 v[22:25], v[140:143], v[236:239], v[22:25]
	v_mfma_f32_16x16x32_bf16 v[14:17], v[152:155], v[236:239], 0
	v_mfma_f32_16x16x32_bf16 v[14:17], v[156:159], v[240:243], v[14:17]
	v_mfma_f32_16x16x32_bf16 v[30:33], v[156:159], v[232:235], 0
	v_mfma_f32_16x16x32_bf16 v[30:33], v[152:155], v[228:231], v[30:33]
	v_mfma_f32_16x16x32_bf16 v[46:49], v[152:155], v[202:205], 0
	v_mfma_f32_16x16x32_bf16 v[46:49], v[156:159], v[206:209], v[46:49]
	v_mfma_f32_16x16x32_bf16 v[58:61], v[156:159], v[198:201], 0
	v_mfma_f32_16x16x32_bf16 v[58:61], v[152:155], v[194:197], v[58:61]
	v_mfma_f32_16x16x32_bf16 v[50:53], v[160:163], v[194:197], 0
	v_mfma_f32_16x16x32_bf16 v[50:53], v[164:167], v[198:201], v[50:53]
	v_mfma_f32_16x16x32_bf16 v[34:37], v[164:167], v[206:209], 0
	v_mfma_f32_16x16x32_bf16 v[34:37], v[160:163], v[202:205], v[34:37]
	v_mfma_f32_16x16x32_bf16 v[18:21], v[160:163], v[228:231], 0
	v_mfma_f32_16x16x32_bf16 v[18:21], v[164:167], v[232:235], v[18:21]
	v_mfma_f32_16x16x32_bf16 v[6:9], v[164:167], v[240:243], 0
	v_mfma_f32_16x16x32_bf16 v[6:9], v[160:163], v[236:239], v[6:9]
	v_mfma_f32_16x16x32_bf16 v[2:5], v[168:171], v[236:239], 0
	v_mfma_f32_16x16x32_bf16 v[2:5], v[190:193], v[240:243], v[2:5]
	v_mfma_f32_16x16x32_bf16 v[10:13], v[190:193], v[232:235], 0
	v_mfma_f32_16x16x32_bf16 v[10:13], v[168:171], v[228:231], v[10:13]
	v_mfma_f32_16x16x32_bf16 v[26:29], v[168:171], v[202:205], 0
	v_mfma_f32_16x16x32_bf16 v[26:29], v[190:193], v[206:209], v[26:29]
	v_mfma_f32_16x16x32_bf16 v[42:45], v[190:193], v[198:201], 0
	v_mfma_f32_16x16x32_bf16 v[42:45], v[168:171], v[194:197], v[42:45]
	s_barrier
	s_setprio 0
	s_branch .Lz0_0_1_ret

.LBB0_575:
	s_add_u32 s22, s18, 0xfff00080
	s_addc_u32 s23, s19, -1
	s_add_i32 s53, 0, 0x10000
	s_cmp_eq_u32 s52, 60
	s_cselect_b32 s25, s9, s23
	s_cselect_b32 s24, s48, s22
	v_add_u32_e32 v140, s53, v143
	s_cselect_b32 s23, s7, s51
	s_cselect_b32 s22, s49, s50
	s_add_i32 s56, 0, 0x14000
	ds_read_b128 v[146:149], v140
	ds_read_b128 v[150:153], v140 offset:1024
	ds_read_b128 v[154:157], v140 offset:2048
	ds_read_b128 v[158:161], v140 offset:3072
	v_add_u32_e32 v140, s56, v143
	ds_read_b128 v[162:165], v140
	ds_read_b128 v[166:169], v140 offset:1024
	ds_read_b128 v[170:173], v140 offset:2048
	ds_read_b128 v[178:181], v140 offset:3072
	v_lshl_add_u64 v[140:141], s[18:19], 0, v[136:137]
	s_add_i32 m0, s39, 0xc000
	ds_read_b128 v[190:193], v145
	ds_read_b128 v[194:197], v145 offset:1024
	ds_read_b128 v[198:201], v145 offset:2048
	ds_read_b128 v[202:205], v145 offset:3072
	ds_read_b128 v[206:209], v145 offset:4096
	ds_read_b128 v[228:231], v145 offset:5120
	ds_read_b128 v[232:235], v145 offset:6144
	ds_read_b128 v[236:239], v145 offset:7168
	global_load_lds_dwordx4 v[140:141], off
	v_lshl_add_u64 v[140:141], s[18:19], 0, v[138:139]
	s_add_i32 m0, s39, 0xe000
	s_nop 0
	global_load_lds_dwordx4 v[140:141], off
	s_cmp_eq_u32 s52, -2
	s_cbranch_scc1 .Lz0_1_0
	s_waitcnt vmcnt(8)
	s_waitcnt lgkmcnt(0)
	s_setprio 1
	s_barrier
	v_mfma_f32_16x16x32_bf16 v[126:129], v[146:149], v[190:193], v[126:129]
	v_mfma_f32_16x16x32_bf16 v[126:129], v[150:153], v[194:197], v[126:129]
	v_mfma_f32_16x16x32_bf16 v[118:121], v[150:153], v[202:205], v[118:121]
	v_mfma_f32_16x16x32_bf16 v[118:121], v[146:149], v[198:201], v[118:121]
	v_mfma_f32_16x16x32_bf16 v[102:105], v[146:149], v[206:209], v[102:105]
	v_mfma_f32_16x16x32_bf16 v[102:105], v[150:153], v[228:231], v[102:105]
	v_mfma_f32_16x16x32_bf16 v[86:89], v[150:153], v[236:239], v[86:89]
	v_mfma_f32_16x16x32_bf16 v[86:89], v[146:149], v[232:235], v[86:89]
	v_mfma_f32_16x16x32_bf16 v[78:81], v[154:157], v[232:235], v[78:81]
	v_mfma_f32_16x16x32_bf16 v[78:81], v[158:161], v[236:239], v[78:81]
	v_mfma_f32_16x16x32_bf16 v[94:97], v[158:161], v[228:231], v[94:97]
	v_mfma_f32_16x16x32_bf16 v[94:97], v[154:157], v[206:209], v[94:97]
	v_mfma_f32_16x16x32_bf16 v[110:113], v[154:157], v[198:201], v[110:113]
	v_mfma_f32_16x16x32_bf16 v[110:113], v[158:161], v[202:205], v[110:113]
	v_mfma_f32_16x16x32_bf16 v[122:125], v[158:161], v[194:197], v[122:125]
	v_mfma_f32_16x16x32_bf16 v[122:125], v[154:157], v[190:193], v[122:125]
	v_mfma_f32_16x16x32_bf16 v[114:117], v[162:165], v[190:193], v[114:117]
	v_mfma_f32_16x16x32_bf16 v[114:117], v[166:169], v[194:197], v[114:117]
	v_mfma_f32_16x16x32_bf16 v[98:101], v[166:169], v[202:205], v[98:101]
	v_mfma_f32_16x16x32_bf16 v[98:101], v[162:165], v[198:201], v[98:101]
	v_mfma_f32_16x16x32_bf16 v[82:85], v[162:165], v[206:209], v[82:85]
	v_mfma_f32_16x16x32_bf16 v[82:85], v[166:169], v[228:231], v[82:85]
	v_mfma_f32_16x16x32_bf16 v[70:73], v[166:169], v[236:239], v[70:73]
	v_mfma_f32_16x16x32_bf16 v[70:73], v[162:165], v[232:235], v[70:73]
	v_mfma_f32_16x16x32_bf16 v[66:69], v[170:173], v[232:235], v[66:69]
	v_mfma_f32_16x16x32_bf16 v[66:69], v[178:181], v[236:239], v[66:69]
	v_mfma_f32_16x16x32_bf16 v[74:77], v[178:181], v[228:231], v[74:77]
	v_mfma_f32_16x16x32_bf16 v[74:77], v[170:173], v[206:209], v[74:77]
	v_mfma_f32_16x16x32_bf16 v[90:93], v[170:173], v[198:201], v[90:93]
	v_mfma_f32_16x16x32_bf16 v[90:93], v[178:181], v[202:205], v[90:93]
	v_mfma_f32_16x16x32_bf16 v[106:109], v[178:181], v[194:197], v[106:109]
	v_mfma_f32_16x16x32_bf16 v[106:109], v[170:173], v[190:193], v[106:109]
	s_barrier
	s_setprio 0
.Lz0_1_0_ret:
	s_add_i32 s53, s53, s38
	v_lshl_add_u64 v[140:141], s[22:23], 0, v[0:1]
	s_mov_b32 m0, s53
	ds_read_b128 v[190:193], v145 offset:16384
	ds_read_b128 v[194:197], v145 offset:17408
	ds_read_b128 v[198:201], v145 offset:18432
	ds_read_b128 v[202:205], v145 offset:19456
	ds_read_b128 v[206:209], v145 offset:20480
	ds_read_b128 v[228:231], v145 offset:21504
	ds_read_b128 v[232:235], v145 offset:22528
	ds_read_b128 v[236:239], v145 offset:23552
	global_load_lds_dwordx4 v[140:141], off
	s_add_i32 m0, s53, 0x2000
	s_add_u32 s54, s22, 0x100000
	v_lshl_add_u64 v[186:187], s[22:23], 0, v[130:131]
	s_addc_u32 s55, s23, 0
	s_add_i32 s53, s56, s38
	global_load_lds_dwordx4 v[186:187], off
	v_lshl_add_u64 v[188:189], s[54:55], 0, v[0:1]
	s_mov_b32 m0, s53
	v_lshl_add_u64 v[210:211], s[24:25], 0, v[132:133]
	global_load_lds_dwordx4 v[188:189], off
	v_lshl_add_u64 v[188:189], s[54:55], 0, v[130:131]
	s_add_i32 m0, s53, 0x2000
	s_nop 0
	global_load_lds_dwordx4 v[188:189], off
	v_lshl_add_u64 v[188:189], s[24:25], 0, v[134:135]
	s_mov_b32 m0, s39
	s_nop 0
	global_load_lds_dwordx4 v[188:189], off
	s_mov_b32 m0, s40
	s_nop 0
	global_load_lds_dwordx4 v[210:211], off
	s_cmp_eq_u32 s52, -2
	s_cbranch_scc1 .Lz0_1_1
	s_waitcnt vmcnt(8)
	s_waitcnt lgkmcnt(0)
	s_setprio 1
	s_barrier
	v_mfma_f32_16x16x32_bf16 v[62:65], v[146:149], v[190:193], v[62:65]
	v_mfma_f32_16x16x32_bf16 v[62:65], v[150:153], v[194:197], v[62:65]
	v_mfma_f32_16x16x32_bf16 v[54:57], v[150:153], v[202:205], v[54:57]
	v_mfma_f32_16x16x32_bf16 v[54:57], v[146:149], v[198:201], v[54:57]
	v_mfma_f32_16x16x32_bf16 v[38:41], v[146:149], v[206:209], v[38:41]
	v_mfma_f32_16x16x32_bf16 v[38:41], v[150:153], v[228:231], v[38:41]
	v_mfma_f32_16x16x32_bf16 v[22:25], v[150:153], v[236:239], v[22:25]
	v_mfma_f32_16x16x32_bf16 v[22:25], v[146:149], v[232:235], v[22:25]
	v_mfma_f32_16x16x32_bf16 v[14:17], v[154:157], v[232:235], v[14:17]
	v_mfma_f32_16x16x32_bf16 v[14:17], v[158:161], v[236:239], v[14:17]
	v_mfma_f32_16x16x32_bf16 v[30:33], v[158:161], v[228:231], v[30:33]
	v_mfma_f32_16x16x32_bf16 v[30:33], v[154:157], v[206:209], v[30:33]
	v_mfma_f32_16x16x32_bf16 v[46:49], v[154:157], v[198:201], v[46:49]
	v_mfma_f32_16x16x32_bf16 v[46:49], v[158:161], v[202:205], v[46:49]
	v_mfma_f32_16x16x32_bf16 v[58:61], v[158:161], v[194:197], v[58:61]
	v_mfma_f32_16x16x32_bf16 v[58:61], v[154:157], v[190:193], v[58:61]
	v_mfma_f32_16x16x32_bf16 v[50:53], v[162:165], v[190:193], v[50:53]
	v_mfma_f32_16x16x32_bf16 v[50:53], v[166:169], v[194:197], v[50:53]
	v_mfma_f32_16x16x32_bf16 v[34:37], v[166:169], v[202:205], v[34:37]
	v_mfma_f32_16x16x32_bf16 v[34:37], v[162:165], v[198:201], v[34:37]
	v_mfma_f32_16x16x32_bf16 v[18:21], v[162:165], v[206:209], v[18:21]
	v_mfma_f32_16x16x32_bf16 v[18:21], v[166:169], v[228:231], v[18:21]
	v_mfma_f32_16x16x32_bf16 v[6:9], v[166:169], v[236:239], v[6:9]
	v_mfma_f32_16x16x32_bf16 v[6:9], v[162:165], v[232:235], v[6:9]
	v_mfma_f32_16x16x32_bf16 v[2:5], v[170:173], v[232:235], v[2:5]
	v_mfma_f32_16x16x32_bf16 v[2:5], v[178:181], v[236:239], v[2:5]
	v_mfma_f32_16x16x32_bf16 v[10:13], v[178:181], v[228:231], v[10:13]
	v_mfma_f32_16x16x32_bf16 v[10:13], v[170:173], v[206:209], v[10:13]
	v_mfma_f32_16x16x32_bf16 v[26:29], v[170:173], v[198:201], v[26:29]
	v_mfma_f32_16x16x32_bf16 v[26:29], v[178:181], v[202:205], v[26:29]
	v_mfma_f32_16x16x32_bf16 v[42:45], v[178:181], v[194:197], v[42:45]
	v_mfma_f32_16x16x32_bf16 v[42:45], v[170:173], v[190:193], v[42:45]
	s_barrier
	s_setprio 0

.Lz0_1_0:
	s_waitcnt vmcnt(8)
	s_waitcnt lgkmcnt(0)
	s_setprio 1
	s_barrier
	v_mfma_f32_16x16x32_bf16 v[126:129], v[146:149], v[190:193], 0
	v_mfma_f32_16x16x32_bf16 v[126:129], v[150:153], v[194:197], v[126:129]
	v_mfma_f32_16x16x32_bf16 v[118:121], v[150:153], v[202:205], 0
	v_mfma_f32_16x16x32_bf16 v[118:121], v[146:149], v[198:201], v[118:121]
	v_mfma_f32_16x16x32_bf16 v[102:105], v[146:149], v[206:209], 0
	v_mfma_f32_16x16x32_bf16 v[102:105], v[150:153], v[228:231], v[102:105]
	v_mfma_f32_16x16x32_bf16 v[86:89], v[150:153], v[236:239], 0
	v_mfma_f32_16x16x32_bf16 v[86:89], v[146:149], v[232:235], v[86:89]
	v_mfma_f32_16x16x32_bf16 v[78:81], v[154:157], v[232:235], 0
	v_mfma_f32_16x16x32_bf16 v[78:81], v[158:161], v[236:239], v[78:81]
	v_mfma_f32_16x16x32_bf16 v[94:97], v[158:161], v[228:231], 0
	v_mfma_f32_16x16x32_bf16 v[94:97], v[154:157], v[206:209], v[94:97]
	v_mfma_f32_16x16x32_bf16 v[110:113], v[154:157], v[198:201], 0
	v_mfma_f32_16x16x32_bf16 v[110:113], v[158:161], v[202:205], v[110:113]
	v_mfma_f32_16x16x32_bf16 v[122:125], v[158:161], v[194:197], 0
	v_mfma_f32_16x16x32_bf16 v[122:125], v[154:157], v[190:193], v[122:125]
	v_mfma_f32_16x16x32_bf16 v[114:117], v[162:165], v[190:193], 0
	v_mfma_f32_16x16x32_bf16 v[114:117], v[166:169], v[194:197], v[114:117]
	v_mfma_f32_16x16x32_bf16 v[98:101], v[166:169], v[202:205], 0
	v_mfma_f32_16x16x32_bf16 v[98:101], v[162:165], v[198:201], v[98:101]
	v_mfma_f32_16x16x32_bf16 v[82:85], v[162:165], v[206:209], 0
	v_mfma_f32_16x16x32_bf16 v[82:85], v[166:169], v[228:231], v[82:85]
	v_mfma_f32_16x16x32_bf16 v[70:73], v[166:169], v[236:239], 0
	v_mfma_f32_16x16x32_bf16 v[70:73], v[162:165], v[232:235], v[70:73]
	v_mfma_f32_16x16x32_bf16 v[66:69], v[170:173], v[232:235], 0
	v_mfma_f32_16x16x32_bf16 v[66:69], v[178:181], v[236:239], v[66:69]
	v_mfma_f32_16x16x32_bf16 v[74:77], v[178:181], v[228:231], 0
	v_mfma_f32_16x16x32_bf16 v[74:77], v[170:173], v[206:209], v[74:77]
	v_mfma_f32_16x16x32_bf16 v[90:93], v[170:173], v[198:201], 0
	v_mfma_f32_16x16x32_bf16 v[90:93], v[178:181], v[202:205], v[90:93]
	v_mfma_f32_16x16x32_bf16 v[106:109], v[178:181], v[194:197], 0
	v_mfma_f32_16x16x32_bf16 v[106:109], v[170:173], v[190:193], v[106:109]
	s_barrier
	s_setprio 0
	s_branch .Lz0_1_0_ret
.Lz0_1_1:
	s_waitcnt vmcnt(8)
	s_waitcnt lgkmcnt(0)
	s_setprio 1
	s_barrier
	v_mfma_f32_16x16x32_bf16 v[62:65], v[146:149], v[190:193], 0
	v_mfma_f32_16x16x32_bf16 v[62:65], v[150:153], v[194:197], v[62:65]
	v_mfma_f32_16x16x32_bf16 v[54:57], v[150:153], v[202:205], 0
	v_mfma_f32_16x16x32_bf16 v[54:57], v[146:149], v[198:201], v[54:57]
	v_mfma_f32_16x16x32_bf16 v[38:41], v[146:149], v[206:209], 0
	v_mfma_f32_16x16x32_bf16 v[38:41], v[150:153], v[228:231], v[38:41]
	v_mfma_f32_16x16x32_bf16 v[22:25], v[150:153], v[236:239], 0
	v_mfma_f32_16x16x32_bf16 v[22:25], v[146:149], v[232:235], v[22:25]
	v_mfma_f32_16x16x32_bf16 v[14:17], v[154:157], v[232:235], 0
	v_mfma_f32_16x16x32_bf16 v[14:17], v[158:161], v[236:239], v[14:17]
	v_mfma_f32_16x16x32_bf16 v[30:33], v[158:161], v[228:231], 0
	v_mfma_f32_16x16x32_bf16 v[30:33], v[154:157], v[206:209], v[30:33]
	v_mfma_f32_16x16x32_bf16 v[46:49], v[154:157], v[198:201], 0
	v_mfma_f32_16x16x32_bf16 v[46:49], v[158:161], v[202:205], v[46:49]
	v_mfma_f32_16x16x32_bf16 v[58:61], v[158:161], v[194:197], 0
	v_mfma_f32_16x16x32_bf16 v[58:61], v[154:157], v[190:193], v[58:61]
	v_mfma_f32_16x16x32_bf16 v[50:53], v[162:165], v[190:193], 0
	v_mfma_f32_16x16x32_bf16 v[50:53], v[166:169], v[194:197], v[50:53]
	v_mfma_f32_16x16x32_bf16 v[34:37], v[166:169], v[202:205], 0
	v_mfma_f32_16x16x32_bf16 v[34:37], v[162:165], v[198:201], v[34:37]
	v_mfma_f32_16x16x32_bf16 v[18:21], v[162:165], v[206:209], 0
	v_mfma_f32_16x16x32_bf16 v[18:21], v[166:169], v[228:231], v[18:21]
	v_mfma_f32_16x16x32_bf16 v[6:9], v[166:169], v[236:239], 0
	v_mfma_f32_16x16x32_bf16 v[6:9], v[162:165], v[232:235], v[6:9]
	v_mfma_f32_16x16x32_bf16 v[2:5], v[170:173], v[232:235], 0
	v_mfma_f32_16x16x32_bf16 v[2:5], v[178:181], v[236:239], v[2:5]
	v_mfma_f32_16x16x32_bf16 v[10:13], v[178:181], v[228:231], 0
	v_mfma_f32_16x16x32_bf16 v[10:13], v[170:173], v[206:209], v[10:13]
	v_mfma_f32_16x16x32_bf16 v[26:29], v[170:173], v[198:201], 0
	v_mfma_f32_16x16x32_bf16 v[26:29], v[178:181], v[202:205], v[26:29]
	v_mfma_f32_16x16x32_bf16 v[42:45], v[178:181], v[194:197], 0
	v_mfma_f32_16x16x32_bf16 v[42:45], v[170:173], v[190:193], v[42:45]
	s_barrier
	s_setprio 0
	s_branch .Lz0_1_1_ret

.LBB0_721:
	s_add_u32 s18, s16, 0xfff00080
	s_addc_u32 s19, s17, -1
	s_add_i32 s53, 0, 0x10000
	s_cmp_eq_u32 s52, 60
	s_cselect_b32 s23, s7, s19
	s_cselect_b32 s22, s48, s18
	v_add_u32_e32 v140, s53, v143
	s_cselect_b32 s19, s5, s51
	s_cselect_b32 s18, s49, s50
	s_add_i32 s56, 0, 0x14000
	ds_read_b128 v[146:149], v140
	ds_read_b128 v[150:153], v140 offset:1024
	ds_read_b128 v[154:157], v140 offset:2048
	ds_read_b128 v[158:161], v140 offset:3072
	v_add_u32_e32 v140, s56, v143
	ds_read_b128 v[162:165], v140
	ds_read_b128 v[166:169], v140 offset:1024
	ds_read_b128 v[170:173], v140 offset:2048
	ds_read_b128 v[178:181], v140 offset:3072
	v_lshl_add_u64 v[140:141], s[16:17], 0, v[136:137]
	s_add_i32 m0, s31, 0xc000
	ds_read_b128 v[190:193], v145
	ds_read_b128 v[194:197], v145 offset:1024
	ds_read_b128 v[198:201], v145 offset:2048
	ds_read_b128 v[202:205], v145 offset:3072
	ds_read_b128 v[206:209], v145 offset:4096
	ds_read_b128 v[228:231], v145 offset:5120
	ds_read_b128 v[232:235], v145 offset:6144
	ds_read_b128 v[236:239], v145 offset:7168
	global_load_lds_dwordx4 v[140:141], off
	v_lshl_add_u64 v[140:141], s[16:17], 0, v[138:139]
	s_add_i32 m0, s31, 0xe000
	s_nop 0
	global_load_lds_dwordx4 v[140:141], off
	s_cmp_eq_u32 s52, -2
	s_cbranch_scc1 .Lz0_2_0
	s_waitcnt vmcnt(8)
	s_waitcnt lgkmcnt(0)
	s_setprio 1
	s_barrier
	v_mfma_f32_16x16x32_bf16 v[126:129], v[146:149], v[190:193], v[126:129]
	v_mfma_f32_16x16x32_bf16 v[126:129], v[150:153], v[194:197], v[126:129]
	v_mfma_f32_16x16x32_bf16 v[110:113], v[150:153], v[202:205], v[110:113]
	v_mfma_f32_16x16x32_bf16 v[110:113], v[146:149], v[198:201], v[110:113]
	v_mfma_f32_16x16x32_bf16 v[94:97], v[146:149], v[206:209], v[94:97]
	v_mfma_f32_16x16x32_bf16 v[94:97], v[150:153], v[228:231], v[94:97]
	v_mfma_f32_16x16x32_bf16 v[78:81], v[150:153], v[236:239], v[78:81]
	v_mfma_f32_16x16x32_bf16 v[78:81], v[146:149], v[232:235], v[78:81]
	v_mfma_f32_16x16x32_bf16 v[70:73], v[154:157], v[232:235], v[70:73]
	v_mfma_f32_16x16x32_bf16 v[70:73], v[158:161], v[236:239], v[70:73]
	v_mfma_f32_16x16x32_bf16 v[86:89], v[158:161], v[228:231], v[86:89]
	v_mfma_f32_16x16x32_bf16 v[86:89], v[154:157], v[206:209], v[86:89]
	v_mfma_f32_16x16x32_bf16 v[102:105], v[154:157], v[198:201], v[102:105]
	v_mfma_f32_16x16x32_bf16 v[102:105], v[158:161], v[202:205], v[102:105]
	v_mfma_f32_16x16x32_bf16 v[118:121], v[158:161], v[194:197], v[118:121]
	v_mfma_f32_16x16x32_bf16 v[118:121], v[154:157], v[190:193], v[118:121]
	v_mfma_f32_16x16x32_bf16 v[122:125], v[162:165], v[190:193], v[122:125]
	v_mfma_f32_16x16x32_bf16 v[122:125], v[166:169], v[194:197], v[122:125]
	v_mfma_f32_16x16x32_bf16 v[106:109], v[166:169], v[202:205], v[106:109]
	v_mfma_f32_16x16x32_bf16 v[106:109], v[162:165], v[198:201], v[106:109]
	v_mfma_f32_16x16x32_bf16 v[90:93], v[162:165], v[206:209], v[90:93]
	v_mfma_f32_16x16x32_bf16 v[90:93], v[166:169], v[228:231], v[90:93]
	v_mfma_f32_16x16x32_bf16 v[74:77], v[166:169], v[236:239], v[74:77]
	v_mfma_f32_16x16x32_bf16 v[74:77], v[162:165], v[232:235], v[74:77]
	v_mfma_f32_16x16x32_bf16 v[66:69], v[170:173], v[232:235], v[66:69]
	v_mfma_f32_16x16x32_bf16 v[66:69], v[178:181], v[236:239], v[66:69]
	v_mfma_f32_16x16x32_bf16 v[82:85], v[178:181], v[228:231], v[82:85]
	v_mfma_f32_16x16x32_bf16 v[82:85], v[170:173], v[206:209], v[82:85]
	v_mfma_f32_16x16x32_bf16 v[98:101], v[170:173], v[198:201], v[98:101]
	v_mfma_f32_16x16x32_bf16 v[98:101], v[178:181], v[202:205], v[98:101]
	v_mfma_f32_16x16x32_bf16 v[114:117], v[178:181], v[194:197], v[114:117]
	v_mfma_f32_16x16x32_bf16 v[114:117], v[170:173], v[190:193], v[114:117]
	s_barrier
	s_setprio 0
.Lz0_2_0_ret:
	s_add_i32 s53, s53, s26
	v_lshl_add_u64 v[140:141], s[18:19], 0, v[0:1]
	s_mov_b32 m0, s53
	ds_read_b128 v[190:193], v145 offset:16384
	ds_read_b128 v[194:197], v145 offset:17408
	ds_read_b128 v[198:201], v145 offset:18432
	ds_read_b128 v[202:205], v145 offset:19456
	ds_read_b128 v[206:209], v145 offset:20480
	ds_read_b128 v[228:231], v145 offset:21504
	ds_read_b128 v[232:235], v145 offset:22528
	ds_read_b128 v[236:239], v145 offset:23552
	global_load_lds_dwordx4 v[140:141], off
	s_add_i32 m0, s53, 0x2000
	s_add_u32 s54, s18, 0x100000
	v_lshl_add_u64 v[186:187], s[18:19], 0, v[130:131]
	s_addc_u32 s55, s19, 0
	s_add_i32 s53, s56, s26
	global_load_lds_dwordx4 v[186:187], off
	v_lshl_add_u64 v[188:189], s[54:55], 0, v[0:1]
	s_mov_b32 m0, s53
	v_lshl_add_u64 v[210:211], s[22:23], 0, v[132:133]
	global_load_lds_dwordx4 v[188:189], off
	v_lshl_add_u64 v[188:189], s[54:55], 0, v[130:131]
	s_add_i32 m0, s53, 0x2000
	s_nop 0
	global_load_lds_dwordx4 v[188:189], off
	v_lshl_add_u64 v[188:189], s[22:23], 0, v[134:135]
	s_mov_b32 m0, s31
	s_nop 0
	global_load_lds_dwordx4 v[188:189], off
	s_mov_b32 m0, s40
	s_nop 0
	global_load_lds_dwordx4 v[210:211], off
	s_cmp_eq_u32 s52, -2
	s_cbranch_scc1 .Lz0_2_1
	s_waitcnt vmcnt(8)
	s_waitcnt lgkmcnt(0)
	s_setprio 1
	s_barrier
	v_mfma_f32_16x16x32_bf16 v[62:65], v[146:149], v[190:193], v[62:65]
	v_mfma_f32_16x16x32_bf16 v[62:65], v[150:153], v[194:197], v[62:65]
	v_mfma_f32_16x16x32_bf16 v[46:49], v[150:153], v[202:205], v[46:49]
	v_mfma_f32_16x16x32_bf16 v[46:49], v[146:149], v[198:201], v[46:49]
	v_mfma_f32_16x16x32_bf16 v[30:33], v[146:149], v[206:209], v[30:33]
	v_mfma_f32_16x16x32_bf16 v[30:33], v[150:153], v[228:231], v[30:33]
	v_mfma_f32_16x16x32_bf16 v[14:17], v[150:153], v[236:239], v[14:17]
	v_mfma_f32_16x16x32_bf16 v[14:17], v[146:149], v[232:235], v[14:17]
	v_mfma_f32_16x16x32_bf16 v[6:9], v[154:157], v[232:235], v[6:9]
	v_mfma_f32_16x16x32_bf16 v[6:9], v[158:161], v[236:239], v[6:9]
	v_mfma_f32_16x16x32_bf16 v[22:25], v[158:161], v[228:231], v[22:25]
	v_mfma_f32_16x16x32_bf16 v[22:25], v[154:157], v[206:209], v[22:25]
	v_mfma_f32_16x16x32_bf16 v[38:41], v[154:157], v[198:201], v[38:41]
	v_mfma_f32_16x16x32_bf16 v[38:41], v[158:161], v[202:205], v[38:41]
	v_mfma_f32_16x16x32_bf16 v[54:57], v[158:161], v[194:197], v[54:57]
	v_mfma_f32_16x16x32_bf16 v[54:57], v[154:157], v[190:193], v[54:57]
	v_mfma_f32_16x16x32_bf16 v[58:61], v[162:165], v[190:193], v[58:61]
	v_mfma_f32_16x16x32_bf16 v[58:61], v[166:169], v[194:197], v[58:61]
	v_mfma_f32_16x16x32_bf16 v[42:45], v[166:169], v[202:205], v[42:45]
	v_mfma_f32_16x16x32_bf16 v[42:45], v[162:165], v[198:201], v[42:45]
	v_mfma_f32_16x16x32_bf16 v[26:29], v[162:165], v[206:209], v[26:29]
	v_mfma_f32_16x16x32_bf16 v[26:29], v[166:169], v[228:231], v[26:29]
	v_mfma_f32_16x16x32_bf16 v[10:13], v[166:169], v[236:239], v[10:13]
	v_mfma_f32_16x16x32_bf16 v[10:13], v[162:165], v[232:235], v[10:13]
	v_mfma_f32_16x16x32_bf16 v[2:5], v[170:173], v[232:235], v[2:5]
	v_mfma_f32_16x16x32_bf16 v[2:5], v[178:181], v[236:239], v[2:5]
	v_mfma_f32_16x16x32_bf16 v[18:21], v[178:181], v[228:231], v[18:21]
	v_mfma_f32_16x16x32_bf16 v[18:21], v[170:173], v[206:209], v[18:21]
	v_mfma_f32_16x16x32_bf16 v[34:37], v[170:173], v[198:201], v[34:37]
	v_mfma_f32_16x16x32_bf16 v[34:37], v[178:181], v[202:205], v[34:37]
	v_mfma_f32_16x16x32_bf16 v[50:53], v[178:181], v[194:197], v[50:53]
	v_mfma_f32_16x16x32_bf16 v[50:53], v[170:173], v[190:193], v[50:53]
	s_barrier
	s_setprio 0

.Lz0_2_0:
	s_waitcnt vmcnt(8)
	s_waitcnt lgkmcnt(0)
	s_setprio 1
	s_barrier
	v_mfma_f32_16x16x32_bf16 v[126:129], v[146:149], v[190:193], 0
	v_mfma_f32_16x16x32_bf16 v[126:129], v[150:153], v[194:197], v[126:129]
	v_mfma_f32_16x16x32_bf16 v[110:113], v[150:153], v[202:205], 0
	v_mfma_f32_16x16x32_bf16 v[110:113], v[146:149], v[198:201], v[110:113]
	v_mfma_f32_16x16x32_bf16 v[94:97], v[146:149], v[206:209], 0
	v_mfma_f32_16x16x32_bf16 v[94:97], v[150:153], v[228:231], v[94:97]
	v_mfma_f32_16x16x32_bf16 v[78:81], v[150:153], v[236:239], 0
	v_mfma_f32_16x16x32_bf16 v[78:81], v[146:149], v[232:235], v[78:81]
	v_mfma_f32_16x16x32_bf16 v[70:73], v[154:157], v[232:235], 0
	v_mfma_f32_16x16x32_bf16 v[70:73], v[158:161], v[236:239], v[70:73]
	v_mfma_f32_16x16x32_bf16 v[86:89], v[158:161], v[228:231], 0
	v_mfma_f32_16x16x32_bf16 v[86:89], v[154:157], v[206:209], v[86:89]
	v_mfma_f32_16x16x32_bf16 v[102:105], v[154:157], v[198:201], 0
	v_mfma_f32_16x16x32_bf16 v[102:105], v[158:161], v[202:205], v[102:105]
	v_mfma_f32_16x16x32_bf16 v[118:121], v[158:161], v[194:197], 0
	v_mfma_f32_16x16x32_bf16 v[118:121], v[154:157], v[190:193], v[118:121]
	v_mfma_f32_16x16x32_bf16 v[122:125], v[162:165], v[190:193], 0
	v_mfma_f32_16x16x32_bf16 v[122:125], v[166:169], v[194:197], v[122:125]
	v_mfma_f32_16x16x32_bf16 v[106:109], v[166:169], v[202:205], 0
	v_mfma_f32_16x16x32_bf16 v[106:109], v[162:165], v[198:201], v[106:109]
	v_mfma_f32_16x16x32_bf16 v[90:93], v[162:165], v[206:209], 0
	v_mfma_f32_16x16x32_bf16 v[90:93], v[166:169], v[228:231], v[90:93]
	v_mfma_f32_16x16x32_bf16 v[74:77], v[166:169], v[236:239], 0
	v_mfma_f32_16x16x32_bf16 v[74:77], v[162:165], v[232:235], v[74:77]
	v_mfma_f32_16x16x32_bf16 v[66:69], v[170:173], v[232:235], 0
	v_mfma_f32_16x16x32_bf16 v[66:69], v[178:181], v[236:239], v[66:69]
	v_mfma_f32_16x16x32_bf16 v[82:85], v[178:181], v[228:231], 0
	v_mfma_f32_16x16x32_bf16 v[82:85], v[170:173], v[206:209], v[82:85]
	v_mfma_f32_16x16x32_bf16 v[98:101], v[170:173], v[198:201], 0
	v_mfma_f32_16x16x32_bf16 v[98:101], v[178:181], v[202:205], v[98:101]
	v_mfma_f32_16x16x32_bf16 v[114:117], v[178:181], v[194:197], 0
	v_mfma_f32_16x16x32_bf16 v[114:117], v[170:173], v[190:193], v[114:117]
	s_barrier
	s_setprio 0
	s_branch .Lz0_2_0_ret
.Lz0_2_1:
	s_waitcnt vmcnt(8)
	s_waitcnt lgkmcnt(0)
	s_setprio 1
	s_barrier
	v_mfma_f32_16x16x32_bf16 v[62:65], v[146:149], v[190:193], 0
	v_mfma_f32_16x16x32_bf16 v[62:65], v[150:153], v[194:197], v[62:65]
	v_mfma_f32_16x16x32_bf16 v[46:49], v[150:153], v[202:205], 0
	v_mfma_f32_16x16x32_bf16 v[46:49], v[146:149], v[198:201], v[46:49]
	v_mfma_f32_16x16x32_bf16 v[30:33], v[146:149], v[206:209], 0
	v_mfma_f32_16x16x32_bf16 v[30:33], v[150:153], v[228:231], v[30:33]
	v_mfma_f32_16x16x32_bf16 v[14:17], v[150:153], v[236:239], 0
	v_mfma_f32_16x16x32_bf16 v[14:17], v[146:149], v[232:235], v[14:17]
	v_mfma_f32_16x16x32_bf16 v[6:9], v[154:157], v[232:235], 0
	v_mfma_f32_16x16x32_bf16 v[6:9], v[158:161], v[236:239], v[6:9]
	v_mfma_f32_16x16x32_bf16 v[22:25], v[158:161], v[228:231], 0
	v_mfma_f32_16x16x32_bf16 v[22:25], v[154:157], v[206:209], v[22:25]
	v_mfma_f32_16x16x32_bf16 v[38:41], v[154:157], v[198:201], 0
	v_mfma_f32_16x16x32_bf16 v[38:41], v[158:161], v[202:205], v[38:41]
	v_mfma_f32_16x16x32_bf16 v[54:57], v[158:161], v[194:197], 0
	v_mfma_f32_16x16x32_bf16 v[54:57], v[154:157], v[190:193], v[54:57]
	v_mfma_f32_16x16x32_bf16 v[58:61], v[162:165], v[190:193], 0
	v_mfma_f32_16x16x32_bf16 v[58:61], v[166:169], v[194:197], v[58:61]
	v_mfma_f32_16x16x32_bf16 v[42:45], v[166:169], v[202:205], 0
	v_mfma_f32_16x16x32_bf16 v[42:45], v[162:165], v[198:201], v[42:45]
	v_mfma_f32_16x16x32_bf16 v[26:29], v[162:165], v[206:209], 0
	v_mfma_f32_16x16x32_bf16 v[26:29], v[166:169], v[228:231], v[26:29]
	v_mfma_f32_16x16x32_bf16 v[10:13], v[166:169], v[236:239], 0
	v_mfma_f32_16x16x32_bf16 v[10:13], v[162:165], v[232:235], v[10:13]
	v_mfma_f32_16x16x32_bf16 v[2:5], v[170:173], v[232:235], 0
	v_mfma_f32_16x16x32_bf16 v[2:5], v[178:181], v[236:239], v[2:5]
	v_mfma_f32_16x16x32_bf16 v[18:21], v[178:181], v[228:231], 0
	v_mfma_f32_16x16x32_bf16 v[18:21], v[170:173], v[206:209], v[18:21]
	v_mfma_f32_16x16x32_bf16 v[34:37], v[170:173], v[198:201], 0
	v_mfma_f32_16x16x32_bf16 v[34:37], v[178:181], v[202:205], v[34:37]
	v_mfma_f32_16x16x32_bf16 v[50:53], v[178:181], v[194:197], 0
	v_mfma_f32_16x16x32_bf16 v[50:53], v[170:173], v[190:193], v[50:53]
	s_barrier
	s_setprio 0
	s_branch .Lz0_2_1_ret

.LBB0_805:
	s_add_u32 s16, s14, 0x100
	s_addc_u32 s17, s15, 0
	s_add_i32 s49, 0, 0x10000
	s_cmpk_eq_i32 s48, 0xa8
	s_cselect_b32 s23, s5, s17
	s_cselect_b32 s22, s4, s16
	v_add_u32_e32 v140, s49, v143
	s_cselect_b32 s19, s9, s47
	s_cselect_b32 s18, s8, s46
	s_add_i32 s50, 0, 0x14000
	ds_read_b128 v[146:149], v140
	ds_read_b128 v[150:153], v140 offset:1024
	ds_read_b128 v[154:157], v140 offset:2048
	ds_read_b128 v[158:161], v140 offset:3072
	v_add_u32_e32 v140, s50, v143
	ds_read_b128 v[162:165], v140
	ds_read_b128 v[166:169], v140 offset:1024
	ds_read_b128 v[170:173], v140 offset:2048
	ds_read_b128 v[178:181], v140 offset:3072
	v_lshl_add_u64 v[140:141], s[14:15], 0, v[136:137]
	s_add_i32 m0, s31, 0xc000
	ds_read_b128 v[190:193], v145
	ds_read_b128 v[194:197], v145 offset:1024
	ds_read_b128 v[198:201], v145 offset:2048
	ds_read_b128 v[202:205], v145 offset:3072
	ds_read_b128 v[206:209], v145 offset:4096
	ds_read_b128 v[228:231], v145 offset:5120
	ds_read_b128 v[232:235], v145 offset:6144
	ds_read_b128 v[236:239], v145 offset:7168
	global_load_lds_dwordx4 v[140:141], off
	v_lshl_add_u64 v[140:141], s[14:15], 0, v[138:139]
	s_add_i32 m0, s31, 0xe000
	s_nop 0
	global_load_lds_dwordx4 v[140:141], off
	s_cmp_eq_u32 s48, -2
	s_cbranch_scc1 .Lz0_3_0
	s_waitcnt vmcnt(8)
	s_waitcnt lgkmcnt(0)
	s_setprio 1
	s_barrier
	v_mfma_f32_16x16x32_bf16 v[126:129], v[146:149], v[190:193], v[126:129]
	v_mfma_f32_16x16x32_bf16 v[126:129], v[150:153], v[194:197], v[126:129]
	v_mfma_f32_16x16x32_bf16 v[118:121], v[150:153], v[202:205], v[118:121]
	v_mfma_f32_16x16x32_bf16 v[118:121], v[146:149], v[198:201], v[118:121]
	v_mfma_f32_16x16x32_bf16 v[102:105], v[146:149], v[206:209], v[102:105]
	v_mfma_f32_16x16x32_bf16 v[102:105], v[150:153], v[228:231], v[102:105]
	v_mfma_f32_16x16x32_bf16 v[86:89], v[150:153], v[236:239], v[86:89]
	v_mfma_f32_16x16x32_bf16 v[86:89], v[146:149], v[232:235], v[86:89]
	v_mfma_f32_16x16x32_bf16 v[78:81], v[154:157], v[232:235], v[78:81]
	v_mfma_f32_16x16x32_bf16 v[78:81], v[158:161], v[236:239], v[78:81]
	v_mfma_f32_16x16x32_bf16 v[94:97], v[158:161], v[228:231], v[94:97]
	v_mfma_f32_16x16x32_bf16 v[94:97], v[154:157], v[206:209], v[94:97]
	v_mfma_f32_16x16x32_bf16 v[110:113], v[154:157], v[198:201], v[110:113]
	v_mfma_f32_16x16x32_bf16 v[110:113], v[158:161], v[202:205], v[110:113]
	v_mfma_f32_16x16x32_bf16 v[122:125], v[158:161], v[194:197], v[122:125]
	v_mfma_f32_16x16x32_bf16 v[122:125], v[154:157], v[190:193], v[122:125]
	v_mfma_f32_16x16x32_bf16 v[114:117], v[162:165], v[190:193], v[114:117]
	v_mfma_f32_16x16x32_bf16 v[114:117], v[166:169], v[194:197], v[114:117]
	v_mfma_f32_16x16x32_bf16 v[98:101], v[166:169], v[202:205], v[98:101]
	v_mfma_f32_16x16x32_bf16 v[98:101], v[162:165], v[198:201], v[98:101]
	v_mfma_f32_16x16x32_bf16 v[82:85], v[162:165], v[206:209], v[82:85]
	v_mfma_f32_16x16x32_bf16 v[82:85], v[166:169], v[228:231], v[82:85]
	v_mfma_f32_16x16x32_bf16 v[70:73], v[166:169], v[236:239], v[70:73]
	v_mfma_f32_16x16x32_bf16 v[70:73], v[162:165], v[232:235], v[70:73]
	v_mfma_f32_16x16x32_bf16 v[66:69], v[170:173], v[232:235], v[66:69]
	v_mfma_f32_16x16x32_bf16 v[66:69], v[178:181], v[236:239], v[66:69]
	v_mfma_f32_16x16x32_bf16 v[74:77], v[178:181], v[228:231], v[74:77]
	v_mfma_f32_16x16x32_bf16 v[74:77], v[170:173], v[206:209], v[74:77]
	v_mfma_f32_16x16x32_bf16 v[90:93], v[170:173], v[198:201], v[90:93]
	v_mfma_f32_16x16x32_bf16 v[90:93], v[178:181], v[202:205], v[90:93]
	v_mfma_f32_16x16x32_bf16 v[106:109], v[178:181], v[194:197], v[106:109]
	v_mfma_f32_16x16x32_bf16 v[106:109], v[170:173], v[190:193], v[106:109]
	s_barrier
	s_setprio 0
.Lz0_3_0_ret:
	s_add_i32 s14, s49, s26
	v_lshl_add_u64 v[140:141], s[18:19], 0, v[0:1]
	s_mov_b32 m0, s14
	ds_read_b128 v[190:193], v145 offset:16384
	ds_read_b128 v[194:197], v145 offset:17408
	ds_read_b128 v[198:201], v145 offset:18432
	ds_read_b128 v[202:205], v145 offset:19456
	ds_read_b128 v[206:209], v145 offset:20480
	ds_read_b128 v[228:231], v145 offset:21504
	ds_read_b128 v[232:235], v145 offset:22528
	ds_read_b128 v[236:239], v145 offset:23552
	global_load_lds_dwordx4 v[140:141], off
	s_add_i32 m0, s14, 0x2000
	s_add_u32 s14, s18, 0x2b0000
	v_lshl_add_u64 v[186:187], s[18:19], 0, v[130:131]
	s_addc_u32 s15, s19, 0
	s_add_i32 s49, s50, s26
	global_load_lds_dwordx4 v[186:187], off
	v_lshl_add_u64 v[188:189], s[14:15], 0, v[0:1]
	s_mov_b32 m0, s49
	v_lshl_add_u64 v[210:211], s[22:23], 0, v[132:133]
	global_load_lds_dwordx4 v[188:189], off
	v_lshl_add_u64 v[188:189], s[14:15], 0, v[130:131]
	s_add_i32 m0, s49, 0x2000
	s_nop 0
	global_load_lds_dwordx4 v[188:189], off
	v_lshl_add_u64 v[188:189], s[22:23], 0, v[134:135]
	s_mov_b32 m0, s31
	s_nop 0
	global_load_lds_dwordx4 v[188:189], off
	s_mov_b32 m0, s36
	s_nop 0
	global_load_lds_dwordx4 v[210:211], off
	s_cmp_eq_u32 s48, -2
	s_cbranch_scc1 .Lz0_3_1
	s_waitcnt vmcnt(8)
	s_waitcnt lgkmcnt(0)
	s_setprio 1
	s_barrier
	v_mfma_f32_16x16x32_bf16 v[62:65], v[146:149], v[190:193], v[62:65]
	v_mfma_f32_16x16x32_bf16 v[62:65], v[150:153], v[194:197], v[62:65]
	v_mfma_f32_16x16x32_bf16 v[54:57], v[150:153], v[202:205], v[54:57]
	v_mfma_f32_16x16x32_bf16 v[54:57], v[146:149], v[198:201], v[54:57]
	v_mfma_f32_16x16x32_bf16 v[38:41], v[146:149], v[206:209], v[38:41]
	v_mfma_f32_16x16x32_bf16 v[38:41], v[150:153], v[228:231], v[38:41]
	v_mfma_f32_16x16x32_bf16 v[22:25], v[150:153], v[236:239], v[22:25]
	v_mfma_f32_16x16x32_bf16 v[22:25], v[146:149], v[232:235], v[22:25]
	v_mfma_f32_16x16x32_bf16 v[14:17], v[154:157], v[232:235], v[14:17]
	v_mfma_f32_16x16x32_bf16 v[14:17], v[158:161], v[236:239], v[14:17]
	v_mfma_f32_16x16x32_bf16 v[30:33], v[158:161], v[228:231], v[30:33]
	v_mfma_f32_16x16x32_bf16 v[30:33], v[154:157], v[206:209], v[30:33]
	v_mfma_f32_16x16x32_bf16 v[46:49], v[154:157], v[198:201], v[46:49]
	v_mfma_f32_16x16x32_bf16 v[46:49], v[158:161], v[202:205], v[46:49]
	v_mfma_f32_16x16x32_bf16 v[58:61], v[158:161], v[194:197], v[58:61]
	v_mfma_f32_16x16x32_bf16 v[58:61], v[154:157], v[190:193], v[58:61]
	v_mfma_f32_16x16x32_bf16 v[50:53], v[162:165], v[190:193], v[50:53]
	v_mfma_f32_16x16x32_bf16 v[50:53], v[166:169], v[194:197], v[50:53]
	v_mfma_f32_16x16x32_bf16 v[34:37], v[166:169], v[202:205], v[34:37]
	v_mfma_f32_16x16x32_bf16 v[34:37], v[162:165], v[198:201], v[34:37]
	v_mfma_f32_16x16x32_bf16 v[18:21], v[162:165], v[206:209], v[18:21]
	v_mfma_f32_16x16x32_bf16 v[18:21], v[166:169], v[228:231], v[18:21]
	v_mfma_f32_16x16x32_bf16 v[6:9], v[166:169], v[236:239], v[6:9]
	v_mfma_f32_16x16x32_bf16 v[6:9], v[162:165], v[232:235], v[6:9]
	v_mfma_f32_16x16x32_bf16 v[2:5], v[170:173], v[232:235], v[2:5]
	v_mfma_f32_16x16x32_bf16 v[2:5], v[178:181], v[236:239], v[2:5]
	v_mfma_f32_16x16x32_bf16 v[10:13], v[178:181], v[228:231], v[10:13]
	v_mfma_f32_16x16x32_bf16 v[10:13], v[170:173], v[206:209], v[10:13]
	v_mfma_f32_16x16x32_bf16 v[26:29], v[170:173], v[198:201], v[26:29]
	v_mfma_f32_16x16x32_bf16 v[26:29], v[178:181], v[202:205], v[26:29]
	v_mfma_f32_16x16x32_bf16 v[42:45], v[178:181], v[194:197], v[42:45]
	v_mfma_f32_16x16x32_bf16 v[42:45], v[170:173], v[190:193], v[42:45]
	s_barrier
	s_setprio 0
